# o19 + barrier waiters poll the cross-XCD arrival counter for (gen+1)*nXCD (no separate generation bump: one memory hop less per barrier)
# speedup vs baseline: 1.0113x; 1.0113x over previous
.LBB0_152:
	s_or_b64 exec, exec, s[6:7]
	v_cvt_f32_u32_e32 v5, v3
	s_waitcnt vmcnt(0)
	v_readfirstlane_b32 s4, v4
	v_sub_u32_e32 v4, 0, v3
	v_rcp_iflag_f32_e32 v5, v5
	v_add_u32_e32 v6, s4, v2
	v_mul_f32_e32 v5, 0x4f7ffffe, v5
	v_cvt_u32_f32_e32 v5, v5
	v_mul_lo_u32 v2, v4, v5
	v_mul_hi_u32 v2, v5, v2
	v_add_u32_e32 v2, v5, v2
	v_mul_hi_u32 v2, v6, v2
	v_mul_lo_u32 v4, v2, v3
	v_sub_u32_e32 v4, v6, v4
	v_add_u32_e32 v5, 1, v2
	v_cmp_ge_u32_e32 vcc, v4, v3
	s_nop 1
	v_cndmask_b32_e32 v2, v2, v5, vcc
	v_sub_u32_e32 v5, v4, v3
	v_cndmask_b32_e32 v4, v4, v5, vcc
	v_add_u32_e32 v5, 1, v2
	v_cmp_ge_u32_e32 vcc, v4, v3
	v_add_u32_e32 v4, 1, v6
	s_nop 0
	v_cndmask_b32_e32 v2, v2, v5, vcc
	v_mul_lo_u32 v5, v3, v2
	v_add_u32_e32 v3, v5, v3
	v_cmp_ne_u32_e32 vcc, v4, v3
	s_and_saveexec_b64 s[4:5], vcc
	s_xor_b64 s[4:5], exec, s[4:5]
	s_cbranch_execz .LBB0_166
	s_waitcnt lgkmcnt(0)
	v_add_u32_e32 v2, 1, v2
	v_mul_lo_u32 v2, v2, v1
	v_mov_b32_e32 v1, 0x3400
	global_load_dword v1, v1, s[86:87] sc1
	s_add_u32 s8, s86, 0x3400
	s_addc_u32 s9, s87, 0
	s_waitcnt vmcnt(0)
	v_cmp_lt_u32_e32 vcc, v1, v2
	s_and_saveexec_b64 s[6:7], vcc
	s_cbranch_execz .LBB0_165
	s_mov_b32 s26, 1
	s_mov_b64 s[10:11], 0
	v_mov_b32_e32 v1, 0
	s_branch .LBB0_156

.LBB0_158:
	global_load_dword v3, v1, s[8:9] sc1
	s_add_i32 s26, s26, 1
	s_mov_b64 s[16:17], -1
	s_waitcnt vmcnt(0)
	v_cmp_ge_u32_e32 vcc, v3, v2
	s_orn2_b64 s[14:15], vcc, exec
	s_branch .LBB0_155

.LBB0_169:
	s_or_b64 exec, exec, s[6:7]
	v_cvt_f32_u32_e32 v4, v1
	s_waitcnt vmcnt(0)
	v_readfirstlane_b32 s4, v3
	s_add_u32 s6, s86, 0x3400
	s_addc_u32 s7, s87, 0
	v_rcp_iflag_f32_e32 v4, v4
	v_add_u32_e32 v2, s4, v2
	v_add_u32_e32 v5, 1, v2
	s_mov_b64 s[8:9], 0
	v_mul_f32_e32 v3, 0x4f7ffffe, v4
	v_cvt_u32_f32_e32 v3, v3
	v_sub_u32_e32 v4, 0, v1
	v_mul_lo_u32 v4, v4, v3
	v_mul_hi_u32 v4, v3, v4
	v_add_u32_e32 v3, v3, v4
	v_mul_hi_u32 v3, v2, v3
	v_mul_lo_u32 v4, v3, v1
	v_sub_u32_e32 v2, v2, v4
	v_add_u32_e32 v6, 1, v3
	v_cmp_ge_u32_e32 vcc, v2, v1
	v_sub_u32_e32 v4, v2, v1
	s_nop 0
	v_cndmask_b32_e32 v3, v3, v6, vcc
	v_cndmask_b32_e32 v2, v2, v4, vcc
	v_add_u32_e32 v4, 1, v3
	v_cmp_ge_u32_e32 vcc, v2, v1
	s_nop 1
	v_cndmask_b32_e32 v4, v3, v4, vcc
	v_mul_lo_u32 v2, v1, v4
	v_add_u32_e32 v1, v2, v1
	v_cmp_ne_u32_e32 vcc, v5, v1
	v_mov_b32_e32 v5, v1
	v_mov_b64_e32 v[2:3], s[6:7]
	s_and_saveexec_b64 s[4:5], vcc
	s_cbranch_execz .LBB0_181
	v_mov_b32_e32 v1, 0
	global_load_dword v2, v1, s[6:7] sc1
	s_mov_b64 s[12:13], 0
	s_waitcnt vmcnt(0)
	v_cmp_lt_u32_e32 vcc, v2, v5
	s_and_saveexec_b64 s[10:11], vcc
	s_cbranch_execz .LBB0_180
	s_add_u32 s8, s86, 0x200
	s_addc_u32 s9, s87, 0
	s_mov_b32 s28, 1
	s_branch .LBB0_173

.LBB0_175:
	global_load_dword v2, v1, s[6:7] sc1
	s_add_i32 s28, s28, 1
	s_mov_b64 s[16:17], -1
	s_waitcnt vmcnt(0)
	v_cmp_ge_u32_e32 vcc, v2, v5
	s_orn2_b64 s[26:27], vcc, exec
	s_branch .LBB0_172

.LBB0_228:
	s_or_b64 exec, exec, s[6:7]
	v_cvt_f32_u32_e32 v5, v3
	s_waitcnt vmcnt(0)
	v_readfirstlane_b32 s4, v4
	v_sub_u32_e32 v4, 0, v3
	v_rcp_iflag_f32_e32 v5, v5
	v_add_u32_e32 v6, s4, v2
	v_mul_f32_e32 v5, 0x4f7ffffe, v5
	v_cvt_u32_f32_e32 v5, v5
	v_mul_lo_u32 v2, v4, v5
	v_mul_hi_u32 v2, v5, v2
	v_add_u32_e32 v2, v5, v2
	v_mul_hi_u32 v2, v6, v2
	v_mul_lo_u32 v4, v2, v3
	v_sub_u32_e32 v4, v6, v4
	v_add_u32_e32 v5, 1, v2
	v_cmp_ge_u32_e32 vcc, v4, v3
	s_nop 1
	v_cndmask_b32_e32 v2, v2, v5, vcc
	v_sub_u32_e32 v5, v4, v3
	v_cndmask_b32_e32 v4, v4, v5, vcc
	v_add_u32_e32 v5, 1, v2
	v_cmp_ge_u32_e32 vcc, v4, v3
	v_add_u32_e32 v4, 1, v6
	s_nop 0
	v_cndmask_b32_e32 v2, v2, v5, vcc
	v_mul_lo_u32 v5, v3, v2
	v_add_u32_e32 v3, v5, v3
	v_cmp_ne_u32_e32 vcc, v4, v3
	s_and_saveexec_b64 s[4:5], vcc
	s_xor_b64 s[4:5], exec, s[4:5]
	s_cbranch_execz .LBB0_242
	s_waitcnt lgkmcnt(0)
	v_add_u32_e32 v2, 1, v2
	v_mul_lo_u32 v2, v2, v1
	v_mov_b32_e32 v1, 0x3400
	global_load_dword v1, v1, s[86:87] sc1
	s_add_u32 s8, s86, 0x3400
	s_addc_u32 s9, s87, 0
	s_waitcnt vmcnt(0)
	v_cmp_lt_u32_e32 vcc, v1, v2
	s_and_saveexec_b64 s[6:7], vcc
	s_cbranch_execz .LBB0_241
	s_mov_b32 s24, 1
	s_mov_b64 s[10:11], 0
	v_mov_b32_e32 v1, 0
	s_branch .LBB0_232

.LBB0_234:
	global_load_dword v3, v1, s[8:9] sc1
	s_add_i32 s24, s24, 1
	s_mov_b64 s[16:17], -1
	s_waitcnt vmcnt(0)
	v_cmp_ge_u32_e32 vcc, v3, v2
	s_orn2_b64 s[14:15], vcc, exec
	s_branch .LBB0_231

.LBB0_245:
	s_or_b64 exec, exec, s[6:7]
	v_cvt_f32_u32_e32 v4, v1
	s_waitcnt vmcnt(0)
	v_readfirstlane_b32 s4, v3
	s_add_u32 s6, s86, 0x3400
	s_addc_u32 s7, s87, 0
	v_rcp_iflag_f32_e32 v4, v4
	v_add_u32_e32 v2, s4, v2
	v_add_u32_e32 v5, 1, v2
	s_mov_b64 s[8:9], 0
	v_mul_f32_e32 v3, 0x4f7ffffe, v4
	v_cvt_u32_f32_e32 v3, v3
	v_sub_u32_e32 v4, 0, v1
	v_mul_lo_u32 v4, v4, v3
	v_mul_hi_u32 v4, v3, v4
	v_add_u32_e32 v3, v3, v4
	v_mul_hi_u32 v3, v2, v3
	v_mul_lo_u32 v4, v3, v1
	v_sub_u32_e32 v2, v2, v4
	v_add_u32_e32 v6, 1, v3
	v_cmp_ge_u32_e32 vcc, v2, v1
	v_sub_u32_e32 v4, v2, v1
	s_nop 0
	v_cndmask_b32_e32 v3, v3, v6, vcc
	v_cndmask_b32_e32 v2, v2, v4, vcc
	v_add_u32_e32 v4, 1, v3
	v_cmp_ge_u32_e32 vcc, v2, v1
	s_nop 1
	v_cndmask_b32_e32 v4, v3, v4, vcc
	v_mul_lo_u32 v2, v1, v4
	v_add_u32_e32 v1, v2, v1
	v_cmp_ne_u32_e32 vcc, v5, v1
	v_mov_b32_e32 v5, v1
	v_mov_b64_e32 v[2:3], s[6:7]
	s_and_saveexec_b64 s[4:5], vcc
	s_cbranch_execz .LBB0_257
	v_mov_b32_e32 v1, 0
	global_load_dword v2, v1, s[6:7] sc1
	s_mov_b64 s[12:13], 0
	s_waitcnt vmcnt(0)
	v_cmp_lt_u32_e32 vcc, v2, v5
	s_and_saveexec_b64 s[10:11], vcc
	s_cbranch_execz .LBB0_256
	s_add_u32 s8, s86, 0x200
	s_addc_u32 s9, s87, 0
	s_mov_b32 s26, 1
	s_branch .LBB0_249

.LBB0_251:
	global_load_dword v2, v1, s[6:7] sc1
	s_add_i32 s26, s26, 1
	s_mov_b64 s[16:17], -1
	s_waitcnt vmcnt(0)
	v_cmp_ge_u32_e32 vcc, v2, v5
	s_orn2_b64 s[24:25], vcc, exec
	s_branch .LBB0_248

.LBB0_334:
	s_or_b64 exec, exec, s[6:7]
	v_cvt_f32_u32_e32 v5, v3
	s_waitcnt vmcnt(0)
	v_readfirstlane_b32 s4, v4
	v_sub_u32_e32 v4, 0, v3
	v_rcp_iflag_f32_e32 v5, v5
	v_add_u32_e32 v6, s4, v2
	v_mul_f32_e32 v5, 0x4f7ffffe, v5
	v_cvt_u32_f32_e32 v5, v5
	v_mul_lo_u32 v2, v4, v5
	v_mul_hi_u32 v2, v5, v2
	v_add_u32_e32 v2, v5, v2
	v_mul_hi_u32 v2, v6, v2
	v_mul_lo_u32 v4, v2, v3
	v_sub_u32_e32 v4, v6, v4
	v_add_u32_e32 v5, 1, v2
	v_cmp_ge_u32_e32 vcc, v4, v3
	s_nop 1
	v_cndmask_b32_e32 v2, v2, v5, vcc
	v_sub_u32_e32 v5, v4, v3
	v_cndmask_b32_e32 v4, v4, v5, vcc
	v_add_u32_e32 v5, 1, v2
	v_cmp_ge_u32_e32 vcc, v4, v3
	v_add_u32_e32 v4, 1, v6
	s_nop 0
	v_cndmask_b32_e32 v2, v2, v5, vcc
	v_mul_lo_u32 v5, v3, v2
	v_add_u32_e32 v3, v5, v3
	v_cmp_ne_u32_e32 vcc, v4, v3
	s_and_saveexec_b64 s[4:5], vcc
	s_xor_b64 s[4:5], exec, s[4:5]
	s_cbranch_execz .LBB0_348
	s_waitcnt lgkmcnt(0)
	v_add_u32_e32 v2, 1, v2
	v_mul_lo_u32 v2, v2, v1
	v_mov_b32_e32 v1, 0x3400
	global_load_dword v1, v1, s[86:87] sc1
	s_add_u32 s8, s86, 0x3400
	s_addc_u32 s9, s87, 0
	s_waitcnt vmcnt(0)
	v_cmp_lt_u32_e32 vcc, v1, v2
	s_and_saveexec_b64 s[6:7], vcc
	s_cbranch_execz .LBB0_347
	s_mov_b32 s22, 1
	s_mov_b64 s[10:11], 0
	v_mov_b32_e32 v1, 0
	s_branch .LBB0_338

.LBB0_340:
	global_load_dword v3, v1, s[8:9] sc1
	s_add_i32 s22, s22, 1
	s_mov_b64 s[16:17], -1
	s_waitcnt vmcnt(0)
	v_cmp_ge_u32_e32 vcc, v3, v2
	s_orn2_b64 s[14:15], vcc, exec
	s_branch .LBB0_337

.LBB0_351:
	s_or_b64 exec, exec, s[6:7]
	v_cvt_f32_u32_e32 v4, v1
	s_waitcnt vmcnt(0)
	v_readfirstlane_b32 s4, v3
	s_add_u32 s6, s86, 0x3400
	s_addc_u32 s7, s87, 0
	v_rcp_iflag_f32_e32 v4, v4
	v_add_u32_e32 v2, s4, v2
	v_add_u32_e32 v5, 1, v2
	s_mov_b64 s[8:9], 0
	v_mul_f32_e32 v3, 0x4f7ffffe, v4
	v_cvt_u32_f32_e32 v3, v3
	v_sub_u32_e32 v4, 0, v1
	v_mul_lo_u32 v4, v4, v3
	v_mul_hi_u32 v4, v3, v4
	v_add_u32_e32 v3, v3, v4
	v_mul_hi_u32 v3, v2, v3
	v_mul_lo_u32 v4, v3, v1
	v_sub_u32_e32 v2, v2, v4
	v_add_u32_e32 v6, 1, v3
	v_cmp_ge_u32_e32 vcc, v2, v1
	v_sub_u32_e32 v4, v2, v1
	s_nop 0
	v_cndmask_b32_e32 v3, v3, v6, vcc
	v_cndmask_b32_e32 v2, v2, v4, vcc
	v_add_u32_e32 v4, 1, v3
	v_cmp_ge_u32_e32 vcc, v2, v1
	s_nop 1
	v_cndmask_b32_e32 v4, v3, v4, vcc
	v_mul_lo_u32 v2, v1, v4
	v_add_u32_e32 v1, v2, v1
	v_cmp_ne_u32_e32 vcc, v5, v1
	v_mov_b32_e32 v5, v1
	v_mov_b64_e32 v[2:3], s[6:7]
	s_and_saveexec_b64 s[4:5], vcc
	s_cbranch_execz .LBB0_363
	v_mov_b32_e32 v1, 0
	global_load_dword v2, v1, s[6:7] sc1
	s_mov_b64 s[12:13], 0
	s_waitcnt vmcnt(0)
	v_cmp_lt_u32_e32 vcc, v2, v5
	s_and_saveexec_b64 s[10:11], vcc
	s_cbranch_execz .LBB0_362
	s_add_u32 s8, s86, 0x200
	s_addc_u32 s9, s87, 0
	s_mov_b32 s24, 1
	s_branch .LBB0_355

.LBB0_357:
	global_load_dword v2, v1, s[6:7] sc1
	s_add_i32 s24, s24, 1
	s_mov_b64 s[16:17], -1
	s_waitcnt vmcnt(0)
	v_cmp_ge_u32_e32 vcc, v2, v5
	s_orn2_b64 s[22:23], vcc, exec
	s_branch .LBB0_354

.LBB0_1188:
	s_or_b64 exec, exec, s[6:7]
	v_cvt_f32_u32_e32 v5, v3
	s_waitcnt vmcnt(0)
	v_readfirstlane_b32 s4, v4
	v_sub_u32_e32 v4, 0, v3
	v_rcp_iflag_f32_e32 v5, v5
	v_add_u32_e32 v6, s4, v2
	v_mul_f32_e32 v5, 0x4f7ffffe, v5
	v_cvt_u32_f32_e32 v5, v5
	v_mul_lo_u32 v2, v4, v5
	v_mul_hi_u32 v2, v5, v2
	v_add_u32_e32 v2, v5, v2
	v_mul_hi_u32 v2, v6, v2
	v_mul_lo_u32 v4, v2, v3
	v_sub_u32_e32 v4, v6, v4
	v_add_u32_e32 v5, 1, v2
	v_cmp_ge_u32_e32 vcc, v4, v3
	s_nop 1
	v_cndmask_b32_e32 v2, v2, v5, vcc
	v_sub_u32_e32 v5, v4, v3
	v_cndmask_b32_e32 v4, v4, v5, vcc
	v_add_u32_e32 v5, 1, v2
	v_cmp_ge_u32_e32 vcc, v4, v3
	v_add_u32_e32 v4, 1, v6
	s_nop 0
	v_cndmask_b32_e32 v2, v2, v5, vcc
	v_mul_lo_u32 v5, v3, v2
	v_add_u32_e32 v3, v5, v3
	v_cmp_ne_u32_e32 vcc, v4, v3
	s_and_saveexec_b64 s[4:5], vcc
	s_xor_b64 s[4:5], exec, s[4:5]
	s_cbranch_execz .LBB0_1202
	s_waitcnt lgkmcnt(0)
	v_add_u32_e32 v2, 1, v2
	v_mul_lo_u32 v2, v2, v1
	v_mov_b32_e32 v1, 0x3400
	global_load_dword v1, v1, s[86:87] sc1
	s_add_u32 s8, s86, 0x3400
	s_addc_u32 s9, s87, 0
	s_waitcnt vmcnt(0)
	v_cmp_lt_u32_e32 vcc, v1, v2
	s_and_saveexec_b64 s[6:7], vcc
	s_cbranch_execz .LBB0_1201
	s_mov_b32 s20, 1
	s_mov_b64 s[10:11], 0
	v_mov_b32_e32 v1, 0
	s_branch .LBB0_1192

.LBB0_1194:
	global_load_dword v3, v1, s[8:9] sc1
	s_add_i32 s20, s20, 1
	s_mov_b64 s[16:17], -1
	s_waitcnt vmcnt(0)
	v_cmp_ge_u32_e32 vcc, v3, v2
	s_orn2_b64 s[14:15], vcc, exec
	s_branch .LBB0_1191

.LBB0_1205:
	s_or_b64 exec, exec, s[6:7]
	v_cvt_f32_u32_e32 v4, v1
	s_waitcnt vmcnt(0)
	v_readfirstlane_b32 s4, v3
	s_add_u32 s6, s86, 0x3400
	s_addc_u32 s7, s87, 0
	v_rcp_iflag_f32_e32 v4, v4
	v_add_u32_e32 v2, s4, v2
	v_add_u32_e32 v5, 1, v2
	s_mov_b64 s[8:9], 0
	v_mul_f32_e32 v3, 0x4f7ffffe, v4
	v_cvt_u32_f32_e32 v3, v3
	v_sub_u32_e32 v4, 0, v1
	v_mul_lo_u32 v4, v4, v3
	v_mul_hi_u32 v4, v3, v4
	v_add_u32_e32 v3, v3, v4
	v_mul_hi_u32 v3, v2, v3
	v_mul_lo_u32 v4, v3, v1
	v_sub_u32_e32 v2, v2, v4
	v_add_u32_e32 v6, 1, v3
	v_cmp_ge_u32_e32 vcc, v2, v1
	v_sub_u32_e32 v4, v2, v1
	s_nop 0
	v_cndmask_b32_e32 v3, v3, v6, vcc
	v_cndmask_b32_e32 v2, v2, v4, vcc
	v_add_u32_e32 v4, 1, v3
	v_cmp_ge_u32_e32 vcc, v2, v1
	s_nop 1
	v_cndmask_b32_e32 v4, v3, v4, vcc
	v_mul_lo_u32 v2, v1, v4
	v_add_u32_e32 v1, v2, v1
	v_cmp_ne_u32_e32 vcc, v5, v1
	v_mov_b32_e32 v5, v1
	v_mov_b64_e32 v[2:3], s[6:7]
	s_and_saveexec_b64 s[4:5], vcc
	s_cbranch_execz .LBB0_1217
	v_mov_b32_e32 v1, 0
	global_load_dword v2, v1, s[6:7] sc1
	s_mov_b64 s[12:13], 0
	s_waitcnt vmcnt(0)
	v_cmp_lt_u32_e32 vcc, v2, v5
	s_and_saveexec_b64 s[10:11], vcc
	s_cbranch_execz .LBB0_1216
	s_add_u32 s8, s86, 0x200
	s_addc_u32 s9, s87, 0
	s_mov_b32 s22, 1
	s_branch .LBB0_1209

.LBB0_1211:
	global_load_dword v2, v1, s[6:7] sc1
	s_add_i32 s22, s22, 1
	s_mov_b64 s[16:17], -1
	s_waitcnt vmcnt(0)
	v_cmp_ge_u32_e32 vcc, v2, v5
	s_orn2_b64 s[20:21], vcc, exec
	s_branch .LBB0_1208

.LBB0_1858:
	s_or_b64 exec, exec, s[6:7]
	v_cvt_f32_u32_e32 v6, v4
	s_waitcnt vmcnt(0)
	v_readfirstlane_b32 s4, v5
	v_sub_u32_e32 v5, 0, v4
	v_rcp_iflag_f32_e32 v6, v6
	v_add_u32_e32 v7, s4, v3
	v_mul_f32_e32 v6, 0x4f7ffffe, v6
	v_cvt_u32_f32_e32 v6, v6
	v_mul_lo_u32 v3, v5, v6
	v_mul_hi_u32 v3, v6, v3
	v_add_u32_e32 v3, v6, v3
	v_mul_hi_u32 v3, v7, v3
	v_mul_lo_u32 v5, v3, v4
	v_sub_u32_e32 v5, v7, v5
	v_add_u32_e32 v6, 1, v3
	v_cmp_ge_u32_e32 vcc, v5, v4
	s_nop 1
	v_cndmask_b32_e32 v3, v3, v6, vcc
	v_sub_u32_e32 v6, v5, v4
	v_cndmask_b32_e32 v5, v5, v6, vcc
	v_add_u32_e32 v6, 1, v3
	v_cmp_ge_u32_e32 vcc, v5, v4
	v_add_u32_e32 v5, 1, v7
	s_nop 0
	v_cndmask_b32_e32 v3, v3, v6, vcc
	v_mul_lo_u32 v6, v4, v3
	v_add_u32_e32 v4, v6, v4
	v_cmp_ne_u32_e32 vcc, v5, v4
	s_and_saveexec_b64 s[4:5], vcc
	s_xor_b64 s[4:5], exec, s[4:5]
	s_cbranch_execz .LBB0_1872
	s_waitcnt lgkmcnt(0)
	v_add_u32_e32 v3, 1, v3
	v_mul_lo_u32 v3, v3, v2
	v_mov_b32_e32 v2, 0x3400
	global_load_dword v2, v2, s[86:87] sc1
	s_add_u32 s8, s86, 0x3400
	s_addc_u32 s9, s87, 0
	s_waitcnt vmcnt(0)
	v_cmp_lt_u32_e32 vcc, v2, v3
	s_and_saveexec_b64 s[6:7], vcc
	s_cbranch_execz .LBB0_1871
	s_mov_b32 s20, 1
	s_mov_b64 s[10:11], 0
	v_mov_b32_e32 v2, 0
	s_branch .LBB0_1862

.LBB0_1864:
	global_load_dword v4, v2, s[8:9] sc1
	s_add_i32 s20, s20, 1
	s_mov_b64 s[16:17], -1
	s_waitcnt vmcnt(0)
	v_cmp_ge_u32_e32 vcc, v4, v3
	s_orn2_b64 s[14:15], vcc, exec
	s_branch .LBB0_1861

.LBB0_1875:
	s_or_b64 exec, exec, s[6:7]
	v_cvt_f32_u32_e32 v5, v2
	s_waitcnt vmcnt(0)
	v_readfirstlane_b32 s4, v4
	s_add_u32 s6, s86, 0x3400
	s_addc_u32 s7, s87, 0
	v_rcp_iflag_f32_e32 v5, v5
	v_add_u32_e32 v3, s4, v3
	v_add_u32_e32 v6, 1, v3
	s_mov_b64 s[8:9], 0
	v_mul_f32_e32 v4, 0x4f7ffffe, v5
	v_cvt_u32_f32_e32 v4, v4
	v_sub_u32_e32 v5, 0, v2
	v_mul_lo_u32 v5, v5, v4
	v_mul_hi_u32 v5, v4, v5
	v_add_u32_e32 v4, v4, v5
	v_mul_hi_u32 v4, v3, v4
	v_mul_lo_u32 v5, v4, v2
	v_sub_u32_e32 v3, v3, v5
	v_add_u32_e32 v7, 1, v4
	v_cmp_ge_u32_e32 vcc, v3, v2
	v_sub_u32_e32 v5, v3, v2
	s_nop 0
	v_cndmask_b32_e32 v4, v4, v7, vcc
	v_cndmask_b32_e32 v3, v3, v5, vcc
	v_add_u32_e32 v5, 1, v4
	v_cmp_ge_u32_e32 vcc, v3, v2
	s_nop 1
	v_cndmask_b32_e32 v4, v4, v5, vcc
	v_mul_lo_u32 v3, v2, v4
	v_add_u32_e32 v2, v3, v2
	v_cmp_ne_u32_e32 vcc, v6, v2
	v_mov_b32_e32 v6, v2
	v_mov_b64_e32 v[2:3], s[6:7]
	s_and_saveexec_b64 s[4:5], vcc
	s_cbranch_execz .LBB0_1887
	v_mov_b32_e32 v2, 0
	global_load_dword v3, v2, s[6:7] sc1
	s_mov_b64 s[12:13], 0
	s_waitcnt vmcnt(0)
	v_cmp_lt_u32_e32 vcc, v3, v6
	s_and_saveexec_b64 s[10:11], vcc
	s_cbranch_execz .LBB0_1886
	s_add_u32 s8, s86, 0x200
	s_addc_u32 s9, s87, 0
	s_mov_b32 s22, 1
	s_branch .LBB0_1879

.LBB0_1881:
	global_load_dword v3, v2, s[6:7] sc1
	s_add_i32 s22, s22, 1
	s_mov_b64 s[16:17], -1
	s_waitcnt vmcnt(0)
	v_cmp_ge_u32_e32 vcc, v3, v6
	s_orn2_b64 s[20:21], vcc, exec
	s_branch .LBB0_1878

.LBB0_2017:
	s_or_b64 exec, exec, s[8:9]
	v_cvt_f32_u32_e32 v6, v4
	s_waitcnt vmcnt(0)
	v_readfirstlane_b32 s6, v5
	v_sub_u32_e32 v5, 0, v4
	v_rcp_iflag_f32_e32 v6, v6
	v_add_u32_e32 v7, s6, v3
	v_mul_f32_e32 v6, 0x4f7ffffe, v6
	v_cvt_u32_f32_e32 v6, v6
	v_mul_lo_u32 v3, v5, v6
	v_mul_hi_u32 v3, v6, v3
	v_add_u32_e32 v3, v6, v3
	v_mul_hi_u32 v3, v7, v3
	v_mul_lo_u32 v5, v3, v4
	v_sub_u32_e32 v5, v7, v5
	v_add_u32_e32 v6, 1, v3
	v_cmp_ge_u32_e32 vcc, v5, v4
	s_nop 1
	v_cndmask_b32_e32 v3, v3, v6, vcc
	v_sub_u32_e32 v6, v5, v4
	v_cndmask_b32_e32 v5, v5, v6, vcc
	v_add_u32_e32 v6, 1, v3
	v_cmp_ge_u32_e32 vcc, v5, v4
	v_add_u32_e32 v5, 1, v7
	s_nop 0
	v_cndmask_b32_e32 v3, v3, v6, vcc
	v_mul_lo_u32 v6, v4, v3
	v_add_u32_e32 v4, v6, v4
	v_cmp_ne_u32_e32 vcc, v5, v4
	s_and_saveexec_b64 s[6:7], vcc
	s_xor_b64 s[6:7], exec, s[6:7]
	s_cbranch_execz .LBB0_2031
	s_waitcnt lgkmcnt(0)
	v_add_u32_e32 v3, 1, v3
	v_mul_lo_u32 v3, v3, v2
	v_mov_b32_e32 v2, 0x3400
	global_load_dword v2, v2, s[86:87] sc1
	s_add_u32 s10, s86, 0x3400
	s_addc_u32 s11, s87, 0
	s_waitcnt vmcnt(0)
	v_cmp_lt_u32_e32 vcc, v2, v3
	s_and_saveexec_b64 s[8:9], vcc
	s_cbranch_execz .LBB0_2030
	s_mov_b32 s22, 1
	s_mov_b64 s[12:13], 0
	v_mov_b32_e32 v2, 0
	s_branch .LBB0_2021

.LBB0_2023:
	global_load_dword v4, v2, s[10:11] sc1
	s_add_i32 s22, s22, 1
	s_mov_b64 s[18:19], -1
	s_waitcnt vmcnt(0)
	v_cmp_ge_u32_e32 vcc, v4, v3
	s_orn2_b64 s[16:17], vcc, exec
	s_branch .LBB0_2020

.LBB0_2034:
	s_or_b64 exec, exec, s[8:9]
	v_cvt_f32_u32_e32 v5, v2
	s_waitcnt vmcnt(0)
	v_readfirstlane_b32 s6, v4
	s_add_u32 s8, s86, 0x3400
	s_addc_u32 s9, s87, 0
	v_rcp_iflag_f32_e32 v5, v5
	v_add_u32_e32 v3, s6, v3
	v_add_u32_e32 v6, 1, v3
	s_mov_b64 s[10:11], 0
	v_mul_f32_e32 v4, 0x4f7ffffe, v5
	v_cvt_u32_f32_e32 v4, v4
	v_sub_u32_e32 v5, 0, v2
	v_mul_lo_u32 v5, v5, v4
	v_mul_hi_u32 v5, v4, v5
	v_add_u32_e32 v4, v4, v5
	v_mul_hi_u32 v4, v3, v4
	v_mul_lo_u32 v5, v4, v2
	v_sub_u32_e32 v3, v3, v5
	v_add_u32_e32 v7, 1, v4
	v_cmp_ge_u32_e32 vcc, v3, v2
	v_sub_u32_e32 v5, v3, v2
	s_nop 0
	v_cndmask_b32_e32 v4, v4, v7, vcc
	v_cndmask_b32_e32 v3, v3, v5, vcc
	v_add_u32_e32 v5, 1, v4
	v_cmp_ge_u32_e32 vcc, v3, v2
	s_nop 1
	v_cndmask_b32_e32 v4, v4, v5, vcc
	v_mul_lo_u32 v3, v2, v4
	v_add_u32_e32 v2, v3, v2
	v_cmp_ne_u32_e32 vcc, v6, v2
	v_mov_b32_e32 v6, v2
	v_mov_b64_e32 v[2:3], s[8:9]
	s_and_saveexec_b64 s[6:7], vcc
	s_cbranch_execz .LBB0_2046
	v_mov_b32_e32 v2, 0
	global_load_dword v3, v2, s[8:9] sc1
	s_mov_b64 s[14:15], 0
	s_waitcnt vmcnt(0)
	v_cmp_lt_u32_e32 vcc, v3, v6
	s_and_saveexec_b64 s[12:13], vcc
	s_cbranch_execz .LBB0_2045
	s_add_u32 s10, s86, 0x200
	s_addc_u32 s11, s87, 0
	s_mov_b32 s24, 1
	s_branch .LBB0_2038

.LBB0_2040:
	global_load_dword v3, v2, s[8:9] sc1
	s_add_i32 s24, s24, 1
	s_mov_b64 s[18:19], -1
	s_waitcnt vmcnt(0)
	v_cmp_ge_u32_e32 vcc, v3, v6
	s_orn2_b64 s[22:23], vcc, exec
	s_branch .LBB0_2037

.LBB0_2242:
	s_or_b64 exec, exec, s[6:7]
	v_cvt_f32_u32_e32 v6, v4
	s_waitcnt vmcnt(0)
	v_readfirstlane_b32 s4, v5
	v_sub_u32_e32 v5, 0, v4
	v_rcp_iflag_f32_e32 v6, v6
	v_add_u32_e32 v7, s4, v3
	v_mul_f32_e32 v6, 0x4f7ffffe, v6
	v_cvt_u32_f32_e32 v6, v6
	v_mul_lo_u32 v3, v5, v6
	v_mul_hi_u32 v3, v6, v3
	v_add_u32_e32 v3, v6, v3
	v_mul_hi_u32 v3, v7, v3
	v_mul_lo_u32 v5, v3, v4
	v_sub_u32_e32 v5, v7, v5
	v_add_u32_e32 v6, 1, v3
	v_cmp_ge_u32_e32 vcc, v5, v4
	s_nop 1
	v_cndmask_b32_e32 v3, v3, v6, vcc
	v_sub_u32_e32 v6, v5, v4
	v_cndmask_b32_e32 v5, v5, v6, vcc
	v_add_u32_e32 v6, 1, v3
	v_cmp_ge_u32_e32 vcc, v5, v4
	v_add_u32_e32 v5, 1, v7
	s_nop 0
	v_cndmask_b32_e32 v3, v3, v6, vcc
	v_mul_lo_u32 v6, v4, v3
	v_add_u32_e32 v4, v6, v4
	v_cmp_ne_u32_e32 vcc, v5, v4
	s_and_saveexec_b64 s[4:5], vcc
	s_xor_b64 s[4:5], exec, s[4:5]
	s_cbranch_execz .LBB0_2256
	s_waitcnt lgkmcnt(0)
	v_add_u32_e32 v3, 1, v3
	v_mul_lo_u32 v3, v3, v2
	v_mov_b32_e32 v2, 0x3400
	global_load_dword v2, v2, s[86:87] sc1
	s_add_u32 s10, s86, 0x3400
	s_addc_u32 s11, s87, 0
	s_waitcnt vmcnt(0)
	v_cmp_lt_u32_e32 vcc, v2, v3
	s_and_saveexec_b64 s[6:7], vcc
	s_cbranch_execz .LBB0_2255
	s_mov_b32 s22, 1
	s_mov_b64 s[12:13], 0
	v_mov_b32_e32 v2, 0
	s_branch .LBB0_2246

.LBB0_2259:
	s_or_b64 exec, exec, s[6:7]
	v_cvt_f32_u32_e32 v5, v2
	s_waitcnt vmcnt(0)
	v_readfirstlane_b32 s4, v4
	s_add_u32 s6, s86, 0x3400
	s_addc_u32 s7, s87, 0
	v_rcp_iflag_f32_e32 v5, v5
	v_add_u32_e32 v3, s4, v3
	v_add_u32_e32 v6, 1, v3
	s_mov_b64 s[10:11], 0
	v_mul_f32_e32 v4, 0x4f7ffffe, v5
	v_cvt_u32_f32_e32 v4, v4
	v_sub_u32_e32 v5, 0, v2
	v_mul_lo_u32 v5, v5, v4
	v_mul_hi_u32 v5, v4, v5
	v_add_u32_e32 v4, v4, v5
	v_mul_hi_u32 v4, v3, v4
	v_mul_lo_u32 v5, v4, v2
	v_sub_u32_e32 v3, v3, v5
	v_add_u32_e32 v7, 1, v4
	v_cmp_ge_u32_e32 vcc, v3, v2
	v_sub_u32_e32 v5, v3, v2
	s_nop 0
	v_cndmask_b32_e32 v4, v4, v7, vcc
	v_cndmask_b32_e32 v3, v3, v5, vcc
	v_add_u32_e32 v5, 1, v4
	v_cmp_ge_u32_e32 vcc, v3, v2
	s_nop 1
	v_cndmask_b32_e32 v4, v4, v5, vcc
	v_mul_lo_u32 v3, v2, v4
	v_add_u32_e32 v2, v3, v2
	v_cmp_ne_u32_e32 vcc, v6, v2
	v_mov_b32_e32 v6, v2
	v_mov_b64_e32 v[2:3], s[6:7]
	s_and_saveexec_b64 s[4:5], vcc
	s_cbranch_execz .LBB0_2271
	v_mov_b32_e32 v2, 0
	global_load_dword v3, v2, s[6:7] sc1
	s_mov_b64 s[14:15], 0
	s_waitcnt vmcnt(0)
	v_cmp_lt_u32_e32 vcc, v3, v6
	s_and_saveexec_b64 s[12:13], vcc
	s_cbranch_execz .LBB0_2270
	s_add_u32 s10, s86, 0x200
	s_addc_u32 s11, s87, 0
	s_mov_b32 s24, 1
	s_branch .LBB0_2263

.LBB0_2265:
	global_load_dword v3, v2, s[6:7] sc1
	s_add_i32 s24, s24, 1
	s_mov_b64 s[18:19], -1
	s_waitcnt vmcnt(0)
	v_cmp_ge_u32_e32 vcc, v3, v6
	s_orn2_b64 s[22:23], vcc, exec
	s_branch .LBB0_2262
